# ssd_passB intra-chunk j-loops (4 copies): ACS/DTS decay inputs read as 4 ds_read_b128 up front instead of 16 waited exec-masked ds_read_b32, masks via v_cndmask, X^T operand reads hoisted before the d
# speedup vs baseline: 1.0150x; 1.0045x over previous
; __device__ __forceinline__ f32x4 mfma32(bf16x8 a, bf16x8 b, f32x4 c) { return __builtin_amdgcn_mfma_f32_16x16x32_bf16(a, b, c, 0, 0, 0); }
; __device__ __forceinline__ bf16x8 pack8(f32x4 a, f32x4 b) { u32x4 w; w.x = pk2(a[0], a[1]); w.y = pk2(a[2], a[3]); w.z = pk2(b[0], b[1]); w.w = pk2(b[2], b[3]); return __builtin_bit_cast(bf16x8, w); }
; __device__ __forceinline__ void ssd_passB(const Ptrs& P, int l, int b, int ch, int gg, unsigned char* lds, int tid, bool dost) {
;     ...
;             for (int j = 0; j <= (lt >> 1); ++j) {
;                 f32x4 cb0 = {0.f, 0.f, 0.f, 0.f}, cb1 = {0.f, 0.f, 0.f, 0.f};
; #pragma unroll
;                 for (int ks = 0; ks < 4; ++ks) { const bf16x8 a0 = *(const bf16x8*)(Bs + (32 * j + lc) * 136 + 32 * ks + 8 * g), a1 = *(const bf16x8*)(Bs + (32 * j + 16 + lc) * 136 + 32 * ks + 8 * g);
;                     cb0 = mfma32(a0, cf[ks], cb0); cb1 = mfma32(a1, cf[ks], cb1); }
; #pragma unroll
;                 for (int r = 0; r < 4; ++r) { const int s0 = 32 * j + 4 * g + r, s1 = s0 + 16;
;                     cb0[r] = (s0 <= li) ? cb0[r] * __expf(Al - ACS[s0]) * DTS[s0] : 0.f;
;                     cb1[r] = (s1 <= li) ? cb1[r] * __expf(Al - ACS[s1]) * DTS[s1] : 0.f; }
;                 const bf16x8 pb = pack8(cb0, cb1);
; #pragma unroll
;                 for (int pt = 0; pt < 4; ++pt) { const int xr = hh * 64 + 16 * pt + lc;
;                     const u32x2 lo = *(const u32x2*)(Xt + sdz(xr, 32 * j + 4 * g)), hi = *(const u32x2*)(Xt + sdz(xr, 32 * j + 16 + 4 * g)); o[pt] = mfma32(cat8(lo, hi), pb, o[pt]); }
;             }
.LBB0_979:
.LBB0_980:
	v_add_u32_e32 v144, v142, v140
	v_add_u32_e32 v145, v141, v140
	v_add_u32_e32 v144, 0x11000, v144
	v_add_u32_e32 v145, 0x22000, v145
	ds_read_b128 v[106:109], v144
	ds_read_b128 v[110:113], v144 offset:4352
	ds_read_b128 v[206:209], v144 offset:64
	ds_read_b128 v[214:217], v144 offset:4416
	ds_read_b128 v[218:221], v145
	ds_read_b128 v[222:225], v145 offset:64
	ds_read_b128 v[226:229], v145 offset:2048
	ds_read_b128 v[230:233], v145 offset:2112
	v_add_u32_e32 v205, 16, v143
	v_sub_u32_e32 v211, v191, v143
	s_waitcnt lgkmcnt(7)
	v_mfma_f32_16x16x32_bf16 v[106:109], v[106:109], v[90:93], 0
	s_waitcnt lgkmcnt(6)
	v_mfma_f32_16x16x32_bf16 v[110:113], v[110:113], v[90:93], 0
	s_waitcnt lgkmcnt(5)
	v_mfma_f32_16x16x32_bf16 v[106:109], v[206:209], v[94:97], v[106:109]
	ds_read_b128 v[206:209], v144 offset:128
	s_waitcnt lgkmcnt(5)
	v_mfma_f32_16x16x32_bf16 v[110:113], v[214:217], v[94:97], v[110:113]
	ds_read_b128 v[214:217], v144 offset:4480
	s_waitcnt lgkmcnt(1)
	v_mfma_f32_16x16x32_bf16 v[106:109], v[206:209], v[98:101], v[106:109]
	ds_read_b128 v[206:209], v144 offset:192
	s_waitcnt lgkmcnt(1)
	v_mfma_f32_16x16x32_bf16 v[110:113], v[214:217], v[98:101], v[110:113]
	ds_read_b128 v[214:217], v144 offset:4544
	v_sub_f32_e32 v218, v128, v218
	v_sub_f32_e32 v219, v128, v219
	v_sub_f32_e32 v220, v128, v220
	v_sub_f32_e32 v221, v128, v221
	v_mul_f32_e32 v218, 0x3fb8aa3b, v218
	v_mul_f32_e32 v219, 0x3fb8aa3b, v219
	v_mul_f32_e32 v220, 0x3fb8aa3b, v220
	v_mul_f32_e32 v221, 0x3fb8aa3b, v221
	v_exp_f32_e32 v218, v218
	v_exp_f32_e32 v219, v219
	v_exp_f32_e32 v220, v220
	v_exp_f32_e32 v221, v221
	v_sub_f32_e32 v222, v128, v222
	v_sub_f32_e32 v223, v128, v223
	v_sub_f32_e32 v224, v128, v224
	v_sub_f32_e32 v225, v128, v225
	v_mul_f32_e32 v222, 0x3fb8aa3b, v222
	v_mul_f32_e32 v223, 0x3fb8aa3b, v223
	v_mul_f32_e32 v224, 0x3fb8aa3b, v224
	v_mul_f32_e32 v225, 0x3fb8aa3b, v225
	v_exp_f32_e32 v222, v222
	v_exp_f32_e32 v223, v223
	v_exp_f32_e32 v224, v224
	v_exp_f32_e32 v225, v225
	s_waitcnt lgkmcnt(1)
	v_mfma_f32_16x16x32_bf16 v[106:109], v[206:209], v[102:105], v[106:109]
	v_xor_b32_e32 v212, v143, v129
	v_xor_b32_e32 v144, v205, v129
	v_lshl_add_u32 v212, v212, 1, v130
	v_lshl_add_u32 v144, v144, 1, v130
	ds_read_b64 v[206:207], v212
	ds_read_b64 v[208:209], v144
	s_waitcnt lgkmcnt(2)
	v_mfma_f32_16x16x32_bf16 v[110:113], v[214:217], v[102:105], v[110:113]
	v_xor_b32_e32 v212, v143, v131
	v_xor_b32_e32 v144, v205, v131
	v_lshl_add_u32 v212, v212, 1, v134
	v_lshl_add_u32 v144, v144, 1, v134
	ds_read_b64 v[214:215], v212
	ds_read_b64 v[216:217], v144
	v_cmp_le_i32_e32 vcc, 0, v211
	v_mul_f32_e32 v106, v106, v218
	v_mul_f32_e32 v106, v226, v106
	v_cndmask_b32_e32 v106, 0, v106, vcc
	v_cmp_le_i32_e32 vcc, 1, v211
	v_mul_f32_e32 v107, v107, v219
	v_mul_f32_e32 v107, v227, v107
	v_cndmask_b32_e32 v107, 0, v107, vcc
	v_cmp_le_i32_e32 vcc, 2, v211
	v_mul_f32_e32 v108, v108, v220
	v_mul_f32_e32 v108, v228, v108
	v_cndmask_b32_e32 v108, 0, v108, vcc
	v_cmp_le_i32_e32 vcc, 3, v211
	v_mul_f32_e32 v109, v109, v221
	v_mul_f32_e32 v109, v229, v109
	v_cndmask_b32_e32 v109, 0, v109, vcc
	v_xor_b32_e32 v212, v143, v135
	v_xor_b32_e32 v144, v205, v135
	v_lshl_add_u32 v212, v212, 1, v136
	v_lshl_add_u32 v144, v144, 1, v136
	ds_read_b64 v[218:219], v212
	ds_read_b64 v[220:221], v144
	v_cmp_le_i32_e32 vcc, 16, v211
	v_mul_f32_e32 v110, v110, v222
	v_mul_f32_e32 v110, v230, v110
	v_cndmask_b32_e32 v110, 0, v110, vcc
	v_cmp_le_i32_e32 vcc, 17, v211
	v_mul_f32_e32 v111, v111, v223
	v_mul_f32_e32 v111, v231, v111
	v_cndmask_b32_e32 v111, 0, v111, vcc
	v_cmp_le_i32_e32 vcc, 18, v211
	v_mul_f32_e32 v112, v112, v224
	v_mul_f32_e32 v112, v232, v112
	v_cndmask_b32_e32 v112, 0, v112, vcc
	v_cmp_le_i32_e32 vcc, 19, v211
	v_mul_f32_e32 v113, v113, v225
	v_mul_f32_e32 v113, v233, v113
	v_cndmask_b32_e32 v113, 0, v113, vcc
	v_xor_b32_e32 v212, v143, v137
	v_xor_b32_e32 v144, v205, v137
	v_lshl_add_u32 v212, v212, 1, v138
	v_lshl_add_u32 v144, v144, 1, v138
	ds_read_b64 v[222:223], v212
	ds_read_b64 v[224:225], v144
	v_cvt_pk_bf16_f32 v106, v106, v107
	v_cvt_pk_bf16_f32 v107, v108, v109
	v_cvt_pk_bf16_f32 v108, v110, v111
	v_cvt_pk_bf16_f32 v109, v112, v113
	v_add_u32_e32 v139, -1, v139
	v_cmp_eq_u32_e32 vcc, 0, v139
	s_waitcnt lgkmcnt(6)
	v_mfma_f32_16x16x32_bf16 v[86:89], v[206:209], v[106:109], v[86:89]
	s_waitcnt lgkmcnt(4)
	v_mfma_f32_16x16x32_bf16 v[82:85], v[214:217], v[106:109], v[82:85]
	s_waitcnt lgkmcnt(2)
	v_mfma_f32_16x16x32_bf16 v[78:81], v[218:221], v[106:109], v[78:81]
	s_waitcnt lgkmcnt(0)
	v_mfma_f32_16x16x32_bf16 v[74:77], v[222:225], v[106:109], v[74:77]
	v_add_u32_e32 v141, 0x80, v141
	v_add_u32_e32 v143, 32, v143
	v_add_u32_e32 v142, 0x2200, v142
	s_or_b64 s[8:9], vcc, s[8:9]
	s_andn2_b64 exec, exec, s[8:9]
	s_cbranch_execnz .LBB0_980
	s_branch .LBB0_996

; __device__ __forceinline__ f32x4 mfma32(bf16x8 a, bf16x8 b, f32x4 c) { return __builtin_amdgcn_mfma_f32_16x16x32_bf16(a, b, c, 0, 0, 0); }
; __device__ __forceinline__ bf16x8 pack8(f32x4 a, f32x4 b) { u32x4 w; w.x = pk2(a[0], a[1]); w.y = pk2(a[2], a[3]); w.z = pk2(b[0], b[1]); w.w = pk2(b[2], b[3]); return __builtin_bit_cast(bf16x8, w); }
; __device__ __forceinline__ void ssd_passB(const Ptrs& P, int l, int b, int ch, int gg, unsigned char* lds, int tid, bool dost) {
;     ...
;             for (int j = 0; j <= (lt >> 1); ++j) {
;                 f32x4 cb0 = {0.f, 0.f, 0.f, 0.f}, cb1 = {0.f, 0.f, 0.f, 0.f};
; #pragma unroll
;                 for (int ks = 0; ks < 4; ++ks) { const bf16x8 a0 = *(const bf16x8*)(Bs + (32 * j + lc) * 136 + 32 * ks + 8 * g), a1 = *(const bf16x8*)(Bs + (32 * j + 16 + lc) * 136 + 32 * ks + 8 * g);
;                     cb0 = mfma32(a0, cf[ks], cb0); cb1 = mfma32(a1, cf[ks], cb1); }
; #pragma unroll
;                 for (int r = 0; r < 4; ++r) { const int s0 = 32 * j + 4 * g + r, s1 = s0 + 16;
;                     cb0[r] = (s0 <= li) ? cb0[r] * __expf(Al - ACS[s0]) * DTS[s0] : 0.f;
;                     cb1[r] = (s1 <= li) ? cb1[r] * __expf(Al - ACS[s1]) * DTS[s1] : 0.f; }
;                 const bf16x8 pb = pack8(cb0, cb1);
; #pragma unroll
;                 for (int pt = 0; pt < 4; ++pt) { const int xr = hh * 64 + 16 * pt + lc;
;                     const u32x2 lo = *(const u32x2*)(Xt + sdz(xr, 32 * j + 4 * g)), hi = *(const u32x2*)(Xt + sdz(xr, 32 * j + 16 + 4 * g)); o[pt] = mfma32(cat8(lo, hi), pb, o[pt]); }
;             }
.LBB0_1003:
.LBB0_1004:
	v_add_u32_e32 v211, v208, v206
	v_add_u32_e32 v212, v207, v206
	v_add_u32_e32 v211, 0x11000, v211
	v_add_u32_e32 v212, 0x22000, v212
	ds_read_b128 v[106:109], v211
	ds_read_b128 v[110:113], v211 offset:4352
	ds_read_b128 v[214:217], v211 offset:64
	ds_read_b128 v[218:221], v211 offset:4416
	ds_read_b128 v[222:225], v212
	ds_read_b128 v[226:229], v212 offset:64
	ds_read_b128 v[230:233], v212 offset:2048
	ds_read_b128 v[244:247], v212 offset:2112
	v_add_u32_e32 v239, 16, v209
	v_sub_u32_e32 v252, v190, v209
	s_waitcnt lgkmcnt(7)
	v_mfma_f32_16x16x32_bf16 v[106:109], v[106:109], v[90:93], 0
	s_waitcnt lgkmcnt(6)
	v_mfma_f32_16x16x32_bf16 v[110:113], v[110:113], v[90:93], 0
	s_waitcnt lgkmcnt(5)
	v_mfma_f32_16x16x32_bf16 v[106:109], v[214:217], v[94:97], v[106:109]
	ds_read_b128 v[214:217], v211 offset:128
	s_waitcnt lgkmcnt(5)
	v_mfma_f32_16x16x32_bf16 v[110:113], v[218:221], v[94:97], v[110:113]
	ds_read_b128 v[218:221], v211 offset:4480
	s_waitcnt lgkmcnt(1)
	v_mfma_f32_16x16x32_bf16 v[106:109], v[214:217], v[98:101], v[106:109]
	ds_read_b128 v[214:217], v211 offset:192
	s_waitcnt lgkmcnt(1)
	v_mfma_f32_16x16x32_bf16 v[110:113], v[218:221], v[98:101], v[110:113]
	ds_read_b128 v[218:221], v211 offset:4544
	v_sub_f32_e32 v222, v156, v222
	v_sub_f32_e32 v223, v156, v223
	v_sub_f32_e32 v224, v156, v224
	v_sub_f32_e32 v225, v156, v225
	v_mul_f32_e32 v222, 0x3fb8aa3b, v222
	v_mul_f32_e32 v223, 0x3fb8aa3b, v223
	v_mul_f32_e32 v224, 0x3fb8aa3b, v224
	v_mul_f32_e32 v225, 0x3fb8aa3b, v225
	v_exp_f32_e32 v222, v222
	v_exp_f32_e32 v223, v223
	v_exp_f32_e32 v224, v224
	v_exp_f32_e32 v225, v225
	v_sub_f32_e32 v226, v156, v226
	v_sub_f32_e32 v227, v156, v227
	v_sub_f32_e32 v228, v156, v228
	v_sub_f32_e32 v229, v156, v229
	v_mul_f32_e32 v226, 0x3fb8aa3b, v226
	v_mul_f32_e32 v227, 0x3fb8aa3b, v227
	v_mul_f32_e32 v228, 0x3fb8aa3b, v228
	v_mul_f32_e32 v229, 0x3fb8aa3b, v229
	v_exp_f32_e32 v226, v226
	v_exp_f32_e32 v227, v227
	v_exp_f32_e32 v228, v228
	v_exp_f32_e32 v229, v229
	s_waitcnt lgkmcnt(1)
	v_mfma_f32_16x16x32_bf16 v[106:109], v[214:217], v[102:105], v[106:109]
	v_xor_b32_e32 v253, v209, v157
	v_xor_b32_e32 v211, v239, v157
	v_lshl_add_u32 v253, v253, 1, v178
	v_lshl_add_u32 v211, v211, 1, v178
	ds_read_b64 v[214:215], v253
	ds_read_b64 v[216:217], v211
	s_waitcnt lgkmcnt(2)
	v_mfma_f32_16x16x32_bf16 v[110:113], v[218:221], v[102:105], v[110:113]
	v_xor_b32_e32 v253, v209, v179
	v_xor_b32_e32 v211, v239, v179
	v_lshl_add_u32 v253, v253, 1, v182
	v_lshl_add_u32 v211, v211, 1, v182
	ds_read_b64 v[218:219], v253
	ds_read_b64 v[220:221], v211
	v_cmp_le_i32_e32 vcc, 0, v252
	v_mul_f32_e32 v106, v106, v222
	v_mul_f32_e32 v106, v230, v106
	v_cndmask_b32_e32 v106, 0, v106, vcc
	v_cmp_le_i32_e32 vcc, 1, v252
	v_mul_f32_e32 v107, v107, v223
	v_mul_f32_e32 v107, v231, v107
	v_cndmask_b32_e32 v107, 0, v107, vcc
	v_cmp_le_i32_e32 vcc, 2, v252
	v_mul_f32_e32 v108, v108, v224
	v_mul_f32_e32 v108, v232, v108
	v_cndmask_b32_e32 v108, 0, v108, vcc
	v_cmp_le_i32_e32 vcc, 3, v252
	v_mul_f32_e32 v109, v109, v225
	v_mul_f32_e32 v109, v233, v109
	v_cndmask_b32_e32 v109, 0, v109, vcc
	v_xor_b32_e32 v253, v209, v183
	v_xor_b32_e32 v211, v239, v183
	v_lshl_add_u32 v253, v253, 1, v186
	v_lshl_add_u32 v211, v211, 1, v186
	ds_read_b64 v[222:223], v253
	ds_read_b64 v[224:225], v211
	v_cmp_le_i32_e32 vcc, 16, v252
	v_mul_f32_e32 v110, v110, v226
	v_mul_f32_e32 v110, v244, v110
	v_cndmask_b32_e32 v110, 0, v110, vcc
	v_cmp_le_i32_e32 vcc, 17, v252
	v_mul_f32_e32 v111, v111, v227
	v_mul_f32_e32 v111, v245, v111
	v_cndmask_b32_e32 v111, 0, v111, vcc
	v_cmp_le_i32_e32 vcc, 18, v252
	v_mul_f32_e32 v112, v112, v228
	v_mul_f32_e32 v112, v246, v112
	v_cndmask_b32_e32 v112, 0, v112, vcc
	v_cmp_le_i32_e32 vcc, 19, v252
	v_mul_f32_e32 v113, v113, v229
	v_mul_f32_e32 v113, v247, v113
	v_cndmask_b32_e32 v113, 0, v113, vcc
	v_xor_b32_e32 v253, v209, v187
	v_xor_b32_e32 v211, v239, v187
	v_lshl_add_u32 v253, v253, 1, v204
	v_lshl_add_u32 v211, v211, 1, v204
	ds_read_b64 v[226:227], v253
	ds_read_b64 v[228:229], v211
	v_cvt_pk_bf16_f32 v106, v106, v107
	v_cvt_pk_bf16_f32 v107, v108, v109
	v_cvt_pk_bf16_f32 v108, v110, v111
	v_cvt_pk_bf16_f32 v109, v112, v113
	v_add_u32_e32 v205, -1, v205
	v_cmp_eq_u32_e32 vcc, 0, v205
	s_waitcnt lgkmcnt(6)
	v_mfma_f32_16x16x32_bf16 v[86:89], v[214:217], v[106:109], v[86:89]
	s_waitcnt lgkmcnt(4)
	v_mfma_f32_16x16x32_bf16 v[82:85], v[218:221], v[106:109], v[82:85]
	s_waitcnt lgkmcnt(2)
	v_mfma_f32_16x16x32_bf16 v[78:81], v[222:225], v[106:109], v[78:81]
	s_waitcnt lgkmcnt(0)
	v_mfma_f32_16x16x32_bf16 v[74:77], v[226:229], v[106:109], v[74:77]
	v_add_u32_e32 v207, 0x80, v207
	v_add_u32_e32 v209, 32, v209
	v_add_u32_e32 v208, 0x2200, v208
	s_or_b64 s[6:7], vcc, s[6:7]
	s_andn2_b64 exec, exec, s[6:7]
	s_cbranch_execnz .LBB0_1004
	s_branch .LBB0_1023

; __device__ __forceinline__ f32x4 mfma32(bf16x8 a, bf16x8 b, f32x4 c) { return __builtin_amdgcn_mfma_f32_16x16x32_bf16(a, b, c, 0, 0, 0); }
; __device__ __forceinline__ bf16x8 pack8(f32x4 a, f32x4 b) { u32x4 w; w.x = pk2(a[0], a[1]); w.y = pk2(a[2], a[3]); w.z = pk2(b[0], b[1]); w.w = pk2(b[2], b[3]); return __builtin_bit_cast(bf16x8, w); }
; __device__ __forceinline__ void ssd_passB(const Ptrs& P, int l, int b, int ch, int gg, unsigned char* lds, int tid, bool dost) {
;     ...
;             for (int j = 0; j <= (lt >> 1); ++j) {
;                 f32x4 cb0 = {0.f, 0.f, 0.f, 0.f}, cb1 = {0.f, 0.f, 0.f, 0.f};
; #pragma unroll
;                 for (int ks = 0; ks < 4; ++ks) { const bf16x8 a0 = *(const bf16x8*)(Bs + (32 * j + lc) * 136 + 32 * ks + 8 * g), a1 = *(const bf16x8*)(Bs + (32 * j + 16 + lc) * 136 + 32 * ks + 8 * g);
;                     cb0 = mfma32(a0, cf[ks], cb0); cb1 = mfma32(a1, cf[ks], cb1); }
; #pragma unroll
;                 for (int r = 0; r < 4; ++r) { const int s0 = 32 * j + 4 * g + r, s1 = s0 + 16;
;                     cb0[r] = (s0 <= li) ? cb0[r] * __expf(Al - ACS[s0]) * DTS[s0] : 0.f;
;                     cb1[r] = (s1 <= li) ? cb1[r] * __expf(Al - ACS[s1]) * DTS[s1] : 0.f; }
;                 const bf16x8 pb = pack8(cb0, cb1);
; #pragma unroll
;                 for (int pt = 0; pt < 4; ++pt) { const int xr = hh * 64 + 16 * pt + lc;
;                     const u32x2 lo = *(const u32x2*)(Xt + sdz(xr, 32 * j + 4 * g)), hi = *(const u32x2*)(Xt + sdz(xr, 32 * j + 16 + 4 * g)); o[pt] = mfma32(cat8(lo, hi), pb, o[pt]); }
;             }
.LBB0_1029:
.LBB0_1030:
	v_add_u32_e32 v219, v217, v215
	v_add_u32_e32 v232, v216, v215
	v_add_u32_e32 v219, 0x11000, v219
	v_add_u32_e32 v232, 0x22000, v232
	ds_read_b128 v[106:109], v219
	ds_read_b128 v[110:113], v219 offset:4352
	ds_read_b128 v[220:223], v219 offset:64
	ds_read_b128 v[224:227], v219 offset:4416
	ds_read_b128 v[228:231], v232
	ds_read_b128 v[244:247], v232 offset:64
	ds_read_b128 v[248:251], v232 offset:2048
	v_add_u32_e32 v233, 16, v218
	v_sub_u32_e32 v239, v188, v218
	s_waitcnt lgkmcnt(6)
	v_mfma_f32_16x16x32_bf16 v[106:109], v[106:109], v[90:93], 0
	s_waitcnt lgkmcnt(5)
	v_mfma_f32_16x16x32_bf16 v[110:113], v[110:113], v[90:93], 0
	s_waitcnt lgkmcnt(4)
	v_mfma_f32_16x16x32_bf16 v[106:109], v[220:223], v[94:97], v[106:109]
	ds_read_b128 v[220:223], v219 offset:128
	s_waitcnt lgkmcnt(4)
	v_mfma_f32_16x16x32_bf16 v[110:113], v[224:227], v[94:97], v[110:113]
	ds_read_b128 v[224:227], v219 offset:4480
	s_waitcnt lgkmcnt(1)
	v_mfma_f32_16x16x32_bf16 v[106:109], v[220:223], v[98:101], v[106:109]
	ds_read_b128 v[220:223], v219 offset:192
	s_waitcnt lgkmcnt(1)
	v_mfma_f32_16x16x32_bf16 v[110:113], v[224:227], v[98:101], v[110:113]
	ds_read_b128 v[224:227], v219 offset:4544
	v_sub_f32_e32 v228, v204, v228
	v_sub_f32_e32 v229, v204, v229
	v_sub_f32_e32 v230, v204, v230
	v_sub_f32_e32 v231, v204, v231
	v_mul_f32_e32 v228, 0x3fb8aa3b, v228
	v_mul_f32_e32 v229, 0x3fb8aa3b, v229
	v_mul_f32_e32 v230, 0x3fb8aa3b, v230
	v_mul_f32_e32 v231, 0x3fb8aa3b, v231
	v_exp_f32_e32 v228, v228
	v_exp_f32_e32 v229, v229
	v_exp_f32_e32 v230, v230
	v_exp_f32_e32 v231, v231
	v_sub_f32_e32 v244, v204, v244
	v_sub_f32_e32 v245, v204, v245
	v_sub_f32_e32 v246, v204, v246
	v_sub_f32_e32 v247, v204, v247
	v_mul_f32_e32 v244, 0x3fb8aa3b, v244
	v_mul_f32_e32 v245, 0x3fb8aa3b, v245
	v_mul_f32_e32 v246, 0x3fb8aa3b, v246
	v_mul_f32_e32 v247, 0x3fb8aa3b, v247
	v_exp_f32_e32 v244, v244
	v_exp_f32_e32 v245, v245
	v_exp_f32_e32 v246, v246
	v_exp_f32_e32 v247, v247
	s_waitcnt lgkmcnt(1)
	v_mfma_f32_16x16x32_bf16 v[106:109], v[220:223], v[102:105], v[106:109]
	v_xor_b32_e32 v252, v218, v203
	v_xor_b32_e32 v219, v233, v203
	v_lshl_add_u32 v252, v252, 1, v205
	v_lshl_add_u32 v219, v219, 1, v205
	ds_read_b64 v[220:221], v252
	ds_read_b64 v[222:223], v219
	s_waitcnt lgkmcnt(2)
	v_mfma_f32_16x16x32_bf16 v[110:113], v[224:227], v[102:105], v[110:113]
	v_xor_b32_e32 v252, v218, v206
	v_xor_b32_e32 v219, v233, v206
	v_lshl_add_u32 v252, v252, 1, v207
	v_lshl_add_u32 v219, v219, 1, v207
	ds_read_b64 v[224:225], v252
	ds_read_b64 v[226:227], v219
	v_cmp_le_i32_e32 vcc, 0, v239
	v_mul_f32_e32 v106, v106, v228
	v_mul_f32_e32 v106, v248, v106
	v_cndmask_b32_e32 v106, 0, v106, vcc
	v_cmp_le_i32_e32 vcc, 1, v239
	v_mul_f32_e32 v107, v107, v229
	v_mul_f32_e32 v107, v249, v107
	v_cndmask_b32_e32 v107, 0, v107, vcc
	v_cmp_le_i32_e32 vcc, 2, v239
	v_mul_f32_e32 v108, v108, v230
	v_mul_f32_e32 v108, v250, v108
	v_cndmask_b32_e32 v108, 0, v108, vcc
	v_cmp_le_i32_e32 vcc, 3, v239
	v_mul_f32_e32 v109, v109, v231
	v_mul_f32_e32 v109, v251, v109
	v_cndmask_b32_e32 v109, 0, v109, vcc
	ds_read_b128 v[248:251], v232 offset:2112
	v_xor_b32_e32 v252, v218, v208
	v_xor_b32_e32 v219, v233, v208
	v_lshl_add_u32 v252, v252, 1, v209
	v_lshl_add_u32 v219, v219, 1, v209
	ds_read_b64 v[228:229], v252
	ds_read_b64 v[230:231], v219
	s_waitcnt lgkmcnt(2)
	v_cmp_le_i32_e32 vcc, 16, v239
	v_mul_f32_e32 v110, v110, v244
	v_mul_f32_e32 v110, v248, v110
	v_cndmask_b32_e32 v110, 0, v110, vcc
	v_cmp_le_i32_e32 vcc, 17, v239
	v_mul_f32_e32 v111, v111, v245
	v_mul_f32_e32 v111, v249, v111
	v_cndmask_b32_e32 v111, 0, v111, vcc
	v_cmp_le_i32_e32 vcc, 18, v239
	v_mul_f32_e32 v112, v112, v246
	v_mul_f32_e32 v112, v250, v112
	v_cndmask_b32_e32 v112, 0, v112, vcc
	v_cmp_le_i32_e32 vcc, 19, v239
	v_mul_f32_e32 v113, v113, v247
	v_mul_f32_e32 v113, v251, v113
	v_cndmask_b32_e32 v113, 0, v113, vcc
	v_xor_b32_e32 v252, v218, v211
	v_xor_b32_e32 v219, v233, v211
	v_lshl_add_u32 v252, v252, 1, v212
	v_lshl_add_u32 v219, v219, 1, v212
	ds_read_b64 v[244:245], v252
	ds_read_b64 v[246:247], v219
	v_cvt_pk_bf16_f32 v106, v106, v107
	v_cvt_pk_bf16_f32 v107, v108, v109
	v_cvt_pk_bf16_f32 v108, v110, v111
	v_cvt_pk_bf16_f32 v109, v112, v113
	v_add_u32_e32 v214, -1, v214
	v_cmp_eq_u32_e32 vcc, 0, v214
	s_waitcnt lgkmcnt(6)
	v_mfma_f32_16x16x32_bf16 v[86:89], v[220:223], v[106:109], v[86:89]
	s_waitcnt lgkmcnt(4)
	v_mfma_f32_16x16x32_bf16 v[82:85], v[224:227], v[106:109], v[82:85]
	s_waitcnt lgkmcnt(2)
	v_mfma_f32_16x16x32_bf16 v[78:81], v[228:231], v[106:109], v[78:81]
	s_waitcnt lgkmcnt(0)
	v_mfma_f32_16x16x32_bf16 v[74:77], v[244:247], v[106:109], v[74:77]
	v_add_u32_e32 v216, 0x80, v216
	v_add_u32_e32 v218, 32, v218
	v_add_u32_e32 v217, 0x2200, v217
	s_or_b64 s[6:7], vcc, s[6:7]
	s_andn2_b64 exec, exec, s[6:7]
	s_cbranch_execnz .LBB0_1030
	s_branch .LBB0_1046

; __device__ __forceinline__ f32x4 mfma32(bf16x8 a, bf16x8 b, f32x4 c) { return __builtin_amdgcn_mfma_f32_16x16x32_bf16(a, b, c, 0, 0, 0); }
; __device__ __forceinline__ bf16x8 pack8(f32x4 a, f32x4 b) { u32x4 w; w.x = pk2(a[0], a[1]); w.y = pk2(a[2], a[3]); w.z = pk2(b[0], b[1]); w.w = pk2(b[2], b[3]); return __builtin_bit_cast(bf16x8, w); }
; __device__ __forceinline__ void ssd_passB(const Ptrs& P, int l, int b, int ch, int gg, unsigned char* lds, int tid, bool dost) {
;     ...
;             for (int j = 0; j <= (lt >> 1); ++j) {
;                 f32x4 cb0 = {0.f, 0.f, 0.f, 0.f}, cb1 = {0.f, 0.f, 0.f, 0.f};
; #pragma unroll
;                 for (int ks = 0; ks < 4; ++ks) { const bf16x8 a0 = *(const bf16x8*)(Bs + (32 * j + lc) * 136 + 32 * ks + 8 * g), a1 = *(const bf16x8*)(Bs + (32 * j + 16 + lc) * 136 + 32 * ks + 8 * g);
;                     cb0 = mfma32(a0, cf[ks], cb0); cb1 = mfma32(a1, cf[ks], cb1); }
; #pragma unroll
;                 for (int r = 0; r < 4; ++r) { const int s0 = 32 * j + 4 * g + r, s1 = s0 + 16;
;                     cb0[r] = (s0 <= li) ? cb0[r] * __expf(Al - ACS[s0]) * DTS[s0] : 0.f;
;                     cb1[r] = (s1 <= li) ? cb1[r] * __expf(Al - ACS[s1]) * DTS[s1] : 0.f; }
;                 const bf16x8 pb = pack8(cb0, cb1);
; #pragma unroll
;                 for (int pt = 0; pt < 4; ++pt) { const int xr = hh * 64 + 16 * pt + lc;
;                     const u32x2 lo = *(const u32x2*)(Xt + sdz(xr, 32 * j + 4 * g)), hi = *(const u32x2*)(Xt + sdz(xr, 32 * j + 16 + 4 * g)); o[pt] = mfma32(cat8(lo, hi), pb, o[pt]); }
;             }
.LBB0_1052:
.LBB0_1053:
	v_add_u32_e32 v68, v58, v56
	v_add_u32_e32 v70, v57, v56
	v_add_u32_e32 v68, 0x11000, v68
	v_add_u32_e32 v70, 0x22000, v70
	ds_read_b128 v[26:29], v68
	ds_read_b128 v[30:33], v68 offset:4352
	ds_read_b128 v[60:63], v68 offset:64
	ds_read_b128 v[64:67], v68 offset:4416
	ds_read_b128 v[94:97], v70
	ds_read_b128 v[98:101], v70 offset:64
	ds_read_b128 v[102:105], v70 offset:2048
	ds_read_b128 v[148:151], v70 offset:2112
	v_add_u32_e32 v72, 16, v59
	v_sub_u32_e32 v73, v121, v59
	s_waitcnt lgkmcnt(7)
	v_mfma_f32_16x16x32_bf16 v[26:29], v[26:29], v[74:77], 0
	s_waitcnt lgkmcnt(6)
	v_mfma_f32_16x16x32_bf16 v[30:33], v[30:33], v[74:77], 0
	s_waitcnt lgkmcnt(5)
	v_mfma_f32_16x16x32_bf16 v[26:29], v[60:63], v[42:45], v[26:29]
	ds_read_b128 v[60:63], v68 offset:128
	s_waitcnt lgkmcnt(5)
	v_mfma_f32_16x16x32_bf16 v[30:33], v[64:67], v[42:45], v[30:33]
	ds_read_b128 v[64:67], v68 offset:4480
	s_waitcnt lgkmcnt(1)
	v_mfma_f32_16x16x32_bf16 v[26:29], v[60:63], v[38:41], v[26:29]
	ds_read_b128 v[60:63], v68 offset:192
	s_waitcnt lgkmcnt(1)
	v_mfma_f32_16x16x32_bf16 v[30:33], v[64:67], v[38:41], v[30:33]
	ds_read_b128 v[64:67], v68 offset:4544
	v_sub_f32_e32 v94, v46, v94
	v_sub_f32_e32 v95, v46, v95
	v_sub_f32_e32 v96, v46, v96
	v_sub_f32_e32 v97, v46, v97
	v_mul_f32_e32 v94, 0x3fb8aa3b, v94
	v_mul_f32_e32 v95, 0x3fb8aa3b, v95
	v_mul_f32_e32 v96, 0x3fb8aa3b, v96
	v_mul_f32_e32 v97, 0x3fb8aa3b, v97
	v_exp_f32_e32 v94, v94
	v_exp_f32_e32 v95, v95
	v_exp_f32_e32 v96, v96
	v_exp_f32_e32 v97, v97
	v_sub_f32_e32 v98, v46, v98
	v_sub_f32_e32 v99, v46, v99
	v_sub_f32_e32 v100, v46, v100
	v_sub_f32_e32 v101, v46, v101
	v_mul_f32_e32 v98, 0x3fb8aa3b, v98
	v_mul_f32_e32 v99, 0x3fb8aa3b, v99
	v_mul_f32_e32 v100, 0x3fb8aa3b, v100
	v_mul_f32_e32 v101, 0x3fb8aa3b, v101
	v_exp_f32_e32 v98, v98
	v_exp_f32_e32 v99, v99
	v_exp_f32_e32 v100, v100
	v_exp_f32_e32 v101, v101
	s_waitcnt lgkmcnt(1)
	v_mfma_f32_16x16x32_bf16 v[26:29], v[60:63], v[34:37], v[26:29]
	v_xor_b32_e32 v106, v59, v47
	v_xor_b32_e32 v68, v72, v47
	v_lshl_add_u32 v106, v106, 1, v48
	v_lshl_add_u32 v68, v68, 1, v48
	ds_read_b64 v[60:61], v106
	ds_read_b64 v[62:63], v68
	s_waitcnt lgkmcnt(2)
	v_mfma_f32_16x16x32_bf16 v[30:33], v[64:67], v[34:37], v[30:33]
	v_xor_b32_e32 v106, v59, v49
	v_xor_b32_e32 v68, v72, v49
	v_lshl_add_u32 v106, v106, 1, v50
	v_lshl_add_u32 v68, v68, 1, v50
	ds_read_b64 v[64:65], v106
	ds_read_b64 v[66:67], v68
	v_cmp_le_i32_e32 vcc, 0, v73
	v_mul_f32_e32 v26, v26, v94
	v_mul_f32_e32 v26, v102, v26
	v_cndmask_b32_e32 v26, 0, v26, vcc
	v_cmp_le_i32_e32 vcc, 1, v73
	v_mul_f32_e32 v27, v27, v95
	v_mul_f32_e32 v27, v103, v27
	v_cndmask_b32_e32 v27, 0, v27, vcc
	v_cmp_le_i32_e32 vcc, 2, v73
	v_mul_f32_e32 v28, v28, v96
	v_mul_f32_e32 v28, v104, v28
	v_cndmask_b32_e32 v28, 0, v28, vcc
	v_cmp_le_i32_e32 vcc, 3, v73
	v_mul_f32_e32 v29, v29, v97
	v_mul_f32_e32 v29, v105, v29
	v_cndmask_b32_e32 v29, 0, v29, vcc
	v_xor_b32_e32 v106, v59, v51
	v_xor_b32_e32 v68, v72, v51
	v_lshl_add_u32 v106, v106, 1, v52
	v_lshl_add_u32 v68, v68, 1, v52
	ds_read_b64 v[94:95], v106
	ds_read_b64 v[96:97], v68
	v_cmp_le_i32_e32 vcc, 16, v73
	v_mul_f32_e32 v30, v30, v98
	v_mul_f32_e32 v30, v148, v30
	v_cndmask_b32_e32 v30, 0, v30, vcc
	v_cmp_le_i32_e32 vcc, 17, v73
	v_mul_f32_e32 v31, v31, v99
	v_mul_f32_e32 v31, v149, v31
	v_cndmask_b32_e32 v31, 0, v31, vcc
	v_cmp_le_i32_e32 vcc, 18, v73
	v_mul_f32_e32 v32, v32, v100
	v_mul_f32_e32 v32, v150, v32
	v_cndmask_b32_e32 v32, 0, v32, vcc
	v_cmp_le_i32_e32 vcc, 19, v73
	v_mul_f32_e32 v33, v33, v101
	v_mul_f32_e32 v33, v151, v33
	v_cndmask_b32_e32 v33, 0, v33, vcc
	v_xor_b32_e32 v106, v59, v53
	v_xor_b32_e32 v68, v72, v53
	v_lshl_add_u32 v106, v106, 1, v54
	v_lshl_add_u32 v68, v68, 1, v54
	ds_read_b64 v[98:99], v106
	ds_read_b64 v[100:101], v68
	v_cvt_pk_bf16_f32 v26, v26, v27
	v_cvt_pk_bf16_f32 v27, v28, v29
	v_cvt_pk_bf16_f32 v28, v30, v31
	v_cvt_pk_bf16_f32 v29, v32, v33
	v_add_u32_e32 v55, -1, v55
	v_cmp_eq_u32_e32 vcc, 0, v55
	s_waitcnt lgkmcnt(6)
	v_mfma_f32_16x16x32_bf16 v[22:25], v[60:63], v[26:29], v[22:25]
	s_waitcnt lgkmcnt(4)
	v_mfma_f32_16x16x32_bf16 v[18:21], v[64:67], v[26:29], v[18:21]
	s_waitcnt lgkmcnt(2)
	v_mfma_f32_16x16x32_bf16 v[12:15], v[94:97], v[26:29], v[12:15]
	s_waitcnt lgkmcnt(0)
	v_mfma_f32_16x16x32_bf16 v[8:11], v[98:101], v[26:29], v[8:11]
	v_add_u32_e32 v57, 0x80, v57
	v_add_u32_e32 v59, 32, v59
	v_add_u32_e32 v58, 0x2200, v58
	s_or_b64 s[6:7], vcc, s[6:7]
	s_andn2_b64 exec, exec, s[6:7]
	s_cbranch_execnz .LBB0_1053
	s_branch .LBB0_1069
